# XCD-local seams: workgroup id = xcc + 8*rank, P1/P4 rows follow the XCD GEMM ownership, five same-XCD seams skip the cross-XCD barrier stage and L2 writeback
# baseline (speedup 1.0000x reference)
_Z8fwd_mega4Args:
	s_load_dword s3, s[0:1], 0xb8
	s_load_dwordx2 s[64:65], s[0:1], 0xb0
	s_load_dwordx2 s[66:67], s[0:1], 0xa0
	s_load_dwordx8 s[56:63], s[0:1], 0x80
	s_add_u32 s24, s0, 0xb0
	v_and_b32_e32 v210, 0x3ff, v0
	s_addc_u32 s25, s1, 0
	v_readfirstlane_b32 s89, v210
	v_cmp_gt_u32_e32 vcc, 16, v210
	s_waitcnt lgkmcnt(0)
	v_writelane_b32 v252, s3, 0
	s_and_saveexec_b64 s[4:5], vcc
	v_lshl_add_u32 v1, v210, 2, 0
	v_add_u32_e32 v1, 0x22000, v1
	v_mov_b32_e32 v2, 0
	ds_write_b32 v1, v2
	s_or_b64 exec, exec, s[4:5]
	s_add_u32 s4, s66, 0x4000
	s_addc_u32 s5, s67, 0
	s_waitcnt lgkmcnt(0)
	s_barrier
	v_writelane_b32 v252, s4, 1
	s_getreg_b32 s3, hwreg(HW_REG_XCC_ID, 0, 4)
	s_and_b32 s3, s3, 15
	v_writelane_b32 v252, s5, 2
	v_cmp_eq_u32_e64 s[38:39], 0, v210
	v_writelane_b32 v252, s3, 3
	s_and_saveexec_b64 s[4:5], s[38:39]
	s_cbranch_execz .LBB0_5
	s_mov_b64 s[6:7], exec
	v_mbcnt_lo_u32_b32 v1, s6, 0
	v_mbcnt_hi_u32_b32 v1, s7, v1
	v_cmp_eq_u32_e32 vcc, 0, v1
	s_and_b64 s[8:9], exec, vcc
	s_mov_b64 exec, s[8:9]
	s_cbranch_execz .LBB0_5
	v_readlane_b32 s3, v252, 3
	s_bcnt1_i32_b64 s6, s[6:7]
	s_lshl_b32 s3, s3, 8
	v_mov_b32_e32 v2, s6
	v_readlane_b32 s6, v252, 1
	v_mov_b32_e32 v1, s3
	v_readlane_b32 s7, v252, 2
	s_nop 4
	global_atomic_add v253, v1, v2, s[6:7] offset:1024 sc0

.Lgs0_238:
	s_or_b64 exec, exec, s[0:1]
	s_waitcnt vmcnt(0)
	s_and_saveexec_b64 s[98:99], s[38:39]
	s_cbranch_execz .Lxl_bc
	v_readlane_b32 s100, v252, 3
	v_mov_b32_e32 v255, 0x2203c
	v_lshl_add_u32 v254, v253, 3, s100
	ds_write_b32 v255, v254
.Lxl_bc:
	s_or_b64 exec, exec, s[98:99]
	s_waitcnt lgkmcnt(0)
	s_barrier
	v_mov_b32_e32 v255, 0x2203c
	ds_read_b32 v254, v255
	s_waitcnt lgkmcnt(0)
	v_readfirstlane_b32 s2, v254
	s_add_u32 s86, s66, 0x200000
	s_addc_u32 s87, s67, 0
	s_and_b32 s0, s2, 7
	s_lshl_b32 s0, s0, 5
	s_lshr_b32 s1, s2, 3
	s_add_i32 s0, s0, s1
	s_lshl_b32 s0, s0, 8
	s_mov_b32 s1, s90
	s_add_i32 s20, s1, s0
	s_cmp_lt_i32 s20, 0x10000
	s_cselect_b64 s[10:11], -1, 0
	s_lshl_b32 s24, s64, 8
	v_mov_b32_e32 v0, v210
	s_and_b64 vcc, exec, s[10:11]
	v_mbcnt_lo_u32_b32 v208, -1, 0
	s_waitcnt lgkmcnt(0)
	s_barrier
	s_cbranch_vccz .LBB0_185
	v_lshlrev_b32_e32 v1, 2, v0
	v_and_b32_e32 v2, 0xfc, v1
	v_mbcnt_hi_u32_b32 v1, -1, v208
	v_and_b32_e32 v3, 64, v1
	v_add_u32_e32 v3, 64, v3
	v_xor_b32_e32 v6, 1, v1
	v_cmp_lt_i32_e32 vcc, v6, v3
	s_ashr_i32 s21, s20, 31
	s_lshl_b64 s[0:1], s[20:21], 11
	v_cndmask_b32_e32 v6, v1, v6, vcc
	v_lshlrev_b32_e32 v72, 2, v6
	v_xor_b32_e32 v6, 2, v1
	v_cmp_lt_i32_e32 vcc, v6, v3
	v_mov_b32_e32 v5, 0
	v_lshlrev_b32_e32 v4, 2, v2
	v_cndmask_b32_e32 v6, v1, v6, vcc
	v_lshlrev_b32_e32 v73, 2, v6
	v_xor_b32_e32 v6, 4, v1
	v_cmp_lt_i32_e32 vcc, v6, v3
	v_and_b32_e32 v0, 63, v0
	s_add_u32 s0, s66, s0
	v_cndmask_b32_e32 v6, v1, v6, vcc
	v_lshlrev_b32_e32 v74, 2, v6
	v_xor_b32_e32 v6, 8, v1
	v_cmp_lt_i32_e32 vcc, v6, v3
	v_lshl_add_u64 v[48:49], s[8:9], 0, v[4:5]
	v_lshl_add_u64 v[50:51], s[16:17], 0, v[4:5]
	v_cndmask_b32_e32 v6, v1, v6, vcc
	v_lshlrev_b32_e32 v75, 2, v6
	v_xor_b32_e32 v6, 16, v1
	v_cmp_lt_i32_e32 vcc, v6, v3
	v_lshlrev_b32_e32 v4, 3, v0
	s_addc_u32 s1, s67, s1
	v_cndmask_b32_e32 v6, v1, v6, vcc
	v_lshlrev_b32_e32 v76, 2, v6
	v_xor_b32_e32 v6, 32, v1
	v_cmp_lt_i32_e32 vcc, v6, v3
	v_or_b32_e32 v8, 0x200, v2
	v_or_b32_e32 v10, 0x300, v2
	v_cndmask_b32_e32 v1, v1, v6, vcc
	v_lshlrev_b32_e32 v77, 2, v1
	v_or_b32_e32 v6, 0x100, v2
	v_lshl_add_u64 v[0:1], s[0:1], 0, v[4:5]
	s_mov_b64 s[0:1], 0x4000400
	s_ashr_i32 s25, s24, 31
	v_lshl_add_u64 v[52:53], v[0:1], 0, s[0:1]
	s_lshl_b64 s[4:5], s[24:25], 11
	v_lshlrev_b32_e32 v78, 2, v2
	v_lshlrev_b32_e32 v79, 2, v6
	v_lshlrev_b32_e32 v80, 2, v8
	v_lshlrev_b32_e32 v81, 2, v10
	v_mov_b32_e32 v82, 0x358637bd
	s_mov_b32 s3, 0xf800000
	v_mov_b32_e32 v83, 0x260
	s_movk_i32 s18, 0x7fff
	s_mov_b32 s19, 0xffff0000
	s_mov_b64 s[6:7], 0x4000
	s_mov_b32 s12, s20
	s_branch .LBB0_181

.LBB0_217:
	s_andn2_saveexec_b64 s[6:7], s[6:7]
	s_cbranch_execz .LBB0_237
	s_mov_b64 s[12:13], exec
	s_branch .LBB0_234
	s_waitcnt lgkmcnt(0)
	s_waitcnt vmcnt(0)
	v_mbcnt_lo_u32_b32 v1, s12, 0
	v_mbcnt_hi_u32_b32 v1, s13, v1
	v_cmp_eq_u32_e32 vcc, 0, v1
	s_and_saveexec_b64 s[14:15], vcc
	s_cbranch_execz .LBB0_220
	s_bcnt1_i32_b64 s3, s[12:13]
	v_mov_b32_e32 v2, 0x7000
	v_mov_b32_e32 v3, s3
	global_atomic_add v2, v2, v3, s[66:67] offset:1024 sc0

.LBB0_286:
	s_andn2_saveexec_b64 s[6:7], s[6:7]
	s_cbranch_execz .LBB0_306
	s_mov_b64 s[12:13], exec
	s_branch .LBB0_303
	s_waitcnt lgkmcnt(0)
	s_waitcnt vmcnt(0)
	v_mbcnt_lo_u32_b32 v1, s12, 0
	v_mbcnt_hi_u32_b32 v1, s13, v1
	v_cmp_eq_u32_e32 vcc, 0, v1
	s_and_saveexec_b64 s[14:15], vcc
	s_cbranch_execz .LBB0_289
	s_bcnt1_i32_b64 s12, s[12:13]
	v_mov_b32_e32 v2, 0x7000
	v_mov_b32_e32 v3, s12
	global_atomic_add v2, v2, v3, s[66:67] offset:1024 sc0

.LBB0_363:
	s_andn2_saveexec_b64 s[6:7], s[6:7]
	s_cbranch_execz .LBB0_383
	s_mov_b64 s[8:9], exec
	s_branch .LBB0_380
	s_waitcnt lgkmcnt(0)
	s_waitcnt vmcnt(0)
	v_mbcnt_lo_u32_b32 v1, s8, 0
	v_mbcnt_hi_u32_b32 v1, s9, v1
	v_cmp_eq_u32_e32 vcc, 0, v1
	s_and_saveexec_b64 s[12:13], vcc
	s_cbranch_execz .LBB0_366
	s_bcnt1_i32_b64 s8, s[8:9]
	v_mov_b32_e32 v2, 0x7000
	v_mov_b32_e32 v3, s8
	global_atomic_add v2, v2, v3, s[66:67] offset:1024 sc0

.LBB0_1086:
	s_andn2_saveexec_b64 s[6:7], s[6:7]
	s_cbranch_execz .LBB0_1106
	s_mov_b64 s[10:11], exec
	s_branch .LBB0_1103
	s_waitcnt lgkmcnt(0)
	s_waitcnt vmcnt(0)
	v_mbcnt_lo_u32_b32 v1, s10, 0
	v_mbcnt_hi_u32_b32 v1, s11, v1
	v_cmp_eq_u32_e32 vcc, 0, v1
	s_and_saveexec_b64 s[12:13], vcc
	s_cbranch_execz .LBB0_1089
	s_bcnt1_i32_b64 s10, s[10:11]
	v_mov_b32_e32 v2, 0x7000
	v_mov_b32_e32 v3, s10
	global_atomic_add v2, v2, v3, s[66:67] offset:1024 sc0

	.amdhsa_kernel _Z8fwd_mega4Args
		.amdhsa_group_segment_fixed_size 0
		.amdhsa_private_segment_fixed_size 0
		.amdhsa_kernarg_size 432
		.amdhsa_user_sgpr_count 2
		.amdhsa_user_sgpr_dispatch_ptr 0
		.amdhsa_user_sgpr_queue_ptr 0
		.amdhsa_user_sgpr_kernarg_segment_ptr 1
		.amdhsa_user_sgpr_dispatch_id 0
		.amdhsa_user_sgpr_kernarg_preload_length 0
		.amdhsa_user_sgpr_kernarg_preload_offset 0
		.amdhsa_user_sgpr_private_segment_size 0
		.amdhsa_uses_dynamic_stack 0
		.amdhsa_enable_private_segment 0
		.amdhsa_system_sgpr_workgroup_id_x 1
		.amdhsa_system_sgpr_workgroup_id_y 0
		.amdhsa_system_sgpr_workgroup_id_z 0
		.amdhsa_system_sgpr_workgroup_info 0
		.amdhsa_system_vgpr_workitem_id 2
		.amdhsa_next_free_vgpr 256
		.amdhsa_next_free_sgpr 102
		.amdhsa_accum_offset 256
		.amdhsa_reserve_vcc 1
		.amdhsa_float_round_mode_32 0
		.amdhsa_float_round_mode_16_64 0
		.amdhsa_float_denorm_mode_32 3
		.amdhsa_float_denorm_mode_16_64 3
		.amdhsa_dx10_clamp 1
		.amdhsa_ieee_mode 1
		.amdhsa_fp16_overflow 0
		.amdhsa_tg_split 0
		.amdhsa_exception_fp_ieee_invalid_op 0
		.amdhsa_exception_fp_denorm_src 0
		.amdhsa_exception_fp_ieee_div_zero 0
		.amdhsa_exception_fp_ieee_overflow 0
		.amdhsa_exception_fp_ieee_underflow 0
		.amdhsa_exception_fp_ieee_inexact 0
		.amdhsa_exception_int_div_zero 0
	.end_amdhsa_kernel

.Lfunc_end0:
	.size	_Z8fwd_mega4Args, .Lfunc_end0-_Z8fwd_mega4Args
	.set _Z8fwd_mega4Args.num_vgpr, 256
	.set _Z8fwd_mega4Args.num_agpr, 0
	.set _Z8fwd_mega4Args.numbered_sgpr, 102
	.set _Z8fwd_mega4Args.num_named_barrier, 0
	.set _Z8fwd_mega4Args.private_seg_size, 0
	.set _Z8fwd_mega4Args.uses_vcc, 1
	.set _Z8fwd_mega4Args.uses_flat_scratch, 0
	.set _Z8fwd_mega4Args.has_dyn_sized_stack, 0
	.set _Z8fwd_mega4Args.has_recursion, 0
	.set _Z8fwd_mega4Args.has_indirect_call, 0

amdhsa.kernels:
  - .agpr_count:     0
    .args:
      - .offset:         0
        .size:           176
        .value_kind:     by_value
      - .offset:         176
        .size:           4
        .value_kind:     hidden_block_count_x
      - .offset:         180
        .size:           4
        .value_kind:     hidden_block_count_y
      - .offset:         184
        .size:           4
        .value_kind:     hidden_block_count_z
      - .offset:         188
        .size:           2
        .value_kind:     hidden_group_size_x
      - .offset:         190
        .size:           2
        .value_kind:     hidden_group_size_y
      - .offset:         192
        .size:           2
        .value_kind:     hidden_group_size_z
      - .offset:         194
        .size:           2
        .value_kind:     hidden_remainder_x
      - .offset:         196
        .size:           2
        .value_kind:     hidden_remainder_y
      - .offset:         198
        .size:           2
        .value_kind:     hidden_remainder_z
      - .offset:         216
        .size:           8
        .value_kind:     hidden_global_offset_x
      - .offset:         224
        .size:           8
        .value_kind:     hidden_global_offset_y
      - .offset:         232
        .size:           8
        .value_kind:     hidden_global_offset_z
      - .offset:         240
        .size:           2
        .value_kind:     hidden_grid_dims
      - .offset:         264
        .size:           8
        .value_kind:     hidden_multigrid_sync_arg
      - .offset:         296
        .size:           4
        .value_kind:     hidden_dynamic_lds_size
    .group_segment_fixed_size: 0
    .kernarg_segment_align: 8
    .kernarg_segment_size: 432
    .language:       OpenCL C
    .language_version:
      - 2
      - 0
    .max_flat_workgroup_size: 512
    .name:           _Z8fwd_mega4Args
    .private_segment_fixed_size: 0
    .sgpr_count:     108
    .sgpr_spill_count: 10
    .symbol:         _Z8fwd_mega4Args.kd
    .uniform_work_group_size: 1
    .uses_dynamic_stack: false
    .vgpr_count:     256
    .vgpr_spill_count: 0
    .wavefront_size: 64
